# grid barrier spin loops: tighter polling s_sleep 1 instead of 2 (shorter barrier exit latency)
# speedup vs baseline: 1.0013x; 1.0013x over previous
; DI void gbar(const Params& p, unsigned& target) {
;     ...
;     while (__hip_atomic_load(bar, __ATOMIC_RELAXED, __HIP_MEMORY_SCOPE_AGENT) < target) __builtin_amdgcn_s_sleep(2);
.LBB0_170:
	s_sleep 1
	global_load_dword v1, v0, s[4:5] sc1
	s_waitcnt vmcnt(0)
	v_cmp_gt_u32_e32 vcc, s97, v1
	s_cbranch_vccnz .LBB0_170

; DI void gbar(const Params& p, unsigned& target) {
;     ...
;     while (__hip_atomic_load(bar, __ATOMIC_RELAXED, __HIP_MEMORY_SCOPE_AGENT) < target) __builtin_amdgcn_s_sleep(2);
.LBB0_189:
	s_sleep 1
	global_load_dword v1, v0, s[4:5] sc1
	s_waitcnt vmcnt(0)
	v_cmp_gt_u32_e32 vcc, s10, v1
	s_cbranch_vccnz .LBB0_189

; DI void gbar(const Params& p, unsigned& target) {
;     ...
;     while (__hip_atomic_load(bar, __ATOMIC_RELAXED, __HIP_MEMORY_SCOPE_AGENT) < target) __builtin_amdgcn_s_sleep(2);
.LBB0_214:
	s_sleep 1
	global_load_dword v0, v1, s[2:3] sc1
	s_waitcnt vmcnt(0)
	v_cmp_gt_u32_e32 vcc, s38, v0
	s_cbranch_vccnz .LBB0_214

; DI void gbar(const Params& p, unsigned& target) {
;     ...
;     while (__hip_atomic_load(bar, __ATOMIC_RELAXED, __HIP_MEMORY_SCOPE_AGENT) < target) __builtin_amdgcn_s_sleep(2);
.LBB0_398:
	s_sleep 1
	global_load_dword v0, v1, s[2:3] sc1
	s_waitcnt vmcnt(0)
	v_cmp_gt_u32_e32 vcc, s8, v0
	s_cbranch_vccnz .LBB0_398

; DI void gbar(const Params& p, unsigned& target) {
;     ...
;     while (__hip_atomic_load(bar, __ATOMIC_RELAXED, __HIP_MEMORY_SCOPE_AGENT) < target) __builtin_amdgcn_s_sleep(2);
.LBB0_784:
	s_sleep 1
	global_load_dword v0, v1, s[2:3] sc1
	s_waitcnt vmcnt(0)
	v_cmp_gt_u32_e32 vcc, s34, v0
	s_cbranch_vccnz .LBB0_784

; DI void gbar(const Params& p, unsigned& target) {
;     ...
;     while (__hip_atomic_load(bar, __ATOMIC_RELAXED, __HIP_MEMORY_SCOPE_AGENT) < target) __builtin_amdgcn_s_sleep(2);
.LBB0_828:
	s_sleep 1
	global_load_dword v0, v1, s[2:3] sc1
	s_waitcnt vmcnt(0)
	v_cmp_gt_u32_e32 vcc, s13, v0
	s_cbranch_vccnz .LBB0_828

; DI void gbar(const Params& p, unsigned& target) {
;     ...
;     while (__hip_atomic_load(bar, __ATOMIC_RELAXED, __HIP_MEMORY_SCOPE_AGENT) < target) __builtin_amdgcn_s_sleep(2);
.LBB0_847:
	s_sleep 1
	global_load_dword v0, v1, s[2:3] sc1
	s_waitcnt vmcnt(0)
	v_cmp_gt_u32_e32 vcc, s29, v0
	s_cbranch_vccnz .LBB0_847

; DI void gbar(const Params& p, unsigned& target) {
;     ...
;     while (__hip_atomic_load(bar, __ATOMIC_RELAXED, __HIP_MEMORY_SCOPE_AGENT) < target) __builtin_amdgcn_s_sleep(2);
.LBB0_866:
	s_sleep 1
	global_load_dword v0, v1, s[2:3] sc1
	s_waitcnt vmcnt(0)
	v_cmp_gt_u32_e32 vcc, s26, v0
	s_cbranch_vccnz .LBB0_866

; DI void gbar(const Params& p, unsigned& target) {
;     ...
;     while (__hip_atomic_load(bar, __ATOMIC_RELAXED, __HIP_MEMORY_SCOPE_AGENT) < target) __builtin_amdgcn_s_sleep(2);
.LBB0_921:
	s_sleep 1
	global_load_dword v0, v1, s[2:3] sc1
	s_waitcnt vmcnt(0)
	v_cmp_gt_u32_e32 vcc, s26, v0
	s_cbranch_vccnz .LBB0_921
	s_branch .Ltramp_192
